# static s_setprio 1 for waves 4-7 (younger half) inside the global attention loop
# baseline (speedup 1.0000x reference)
; __device__ __forceinline__ void attn_global(LAS unsigned char* lds, const bf16_t* __restrict__ PROJ, const bf16_t* __restrict__ VT, bf16_t* __restrict__ AO,
;                                             int rowbase, int S, int hq, int q0, float bound2) {
;     ...
;     int t = 0;
; #pragma unroll 1
;     for (; t + 10 < T; t += 4) { ATT_DSTEP(t, 0, true); ATT_DSTEP(t + 2, 2, true); }
; #pragma unroll 1
;     for (; t < T; t += 4) { ATT_DSTEP(t, 0, false); ATT_DSTEP(t + 2, 2, false); }
.LBB0_206:
	v_readfirstlane_b32 s98, v171
	s_nop 3
	s_cmpk_ge_u32 s98, 0x100
	s_cbranch_scc0 .Lattn_noprio
	s_setprio 1
